# dt/cumsum loop software-pipelined: next item's 4 loads issued before current item's softplus/scan math (was 2 dependent load round trips per item)
# speedup vs baseline: 1.0204x; 1.0011x over previous
; __device__ __forceinline__ void conv_phase(const Params& P, const int pass, const int wvi) {
;     ...
;   const float* dtr = (const float*)(ws + OFF_DTR);
;   float* dtt = (float*)(ws + OFF_DTT);
;   float* cum = (float*)(ws + OFF_CUM);
;   const int lane = tid & 63, wv = __builtin_amdgcn_readfirstlane(tid >> 6);
;   for (int it = blockIdx.x * 8 + wv; it < (PT / 128) * 128; it += gridDim.x * 8) {
;     const int dh = it & 127, ch = it >> 7, dir = dh >> 6;
;     const int tb = ch * 128;
;     const float Ac = -__expf(a_log[dh]);
;     const float db = dt_bias[dh];
;     const int e0 = dir ? (127 - 2 * lane) : (2 * lane), e1 = dir ? (126 - 2 * lane) : (2 * lane + 1);
;     float x0 = dtr[(size_t)(tb + e0) * 128 + dh] + db, x1 = dtr[(size_t)(tb + e1) * 128 + dh] + db;
;     float d0 = fmaxf(x0, 0.f) + log1pf(__expf(-fabsf(x0))), d1 = fmaxf(x1, 0.f) + log1pf(__expf(-fabsf(x1)));
;     float a0 = d0 * Ac, a1 = d1 * Ac;
;     float s = a0 + a1;
; #pragma unroll
;     for (int o = 1; o < 64; o <<= 1) { float v = shfl_src(s, (lane - o) & 63); if (lane >= o) s += v; }
;     dtt[(size_t)dh * PT + tb + e0] = d0; dtt[(size_t)dh * PT + tb + e1] = d1;
;     cum[(size_t)dh * PT + tb + e0] = s - a1; cum[(size_t)dh * PT + tb + e1] = s;
.LBB0_325:
	s_or_b64 exec, exec, s[10:11]
	v_readfirstlane_b32 s0, v121
	s_ashr_i32 s0, s0, 6
	v_readlane_b32 s1, v246, 6
	s_add_i32 s0, s0, s1
	v_readlane_b32 s24, v246, 56
	v_readlane_b32 s22, v246, 60
	v_readlane_b32 s26, v246, 62
	v_readlane_b32 s28, v245, 0
	v_readlane_b32 s34, v245, 2
	s_cmpk_gt_i32 s0, 0x3fff
	v_readlane_b32 s25, v246, 57
	v_readlane_b32 s23, v246, 61
	v_readlane_b32 s27, v246, 63
	v_readlane_b32 s29, v245, 1
	v_readlane_b32 s35, v245, 3
	s_cbranch_scc1 .LBB0_328
	v_and_b32_e32 v11, 63, v120
	v_lshlrev_b32_e32 v10, 2, v120
	s_movk_i32 s1, 0xc0
	v_lshlrev_b32_e32 v0, 1, v11
	v_and_or_b32 v4, v10, s1, 60
	v_add_u32_e32 v5, 0xfc, v10
	v_add_u32_e32 v6, 0xf8, v10
	v_add_u32_e32 v7, 0xf0, v10
	v_add_u32_e32 v8, 0xe0, v10
	v_add_u32_e32 v9, 0xc0, v10
	s_movk_i32 s1, 0x80
	v_readlane_b32 s4, v246, 58
	v_readlane_b32 s36, v243, 33
	v_xor_b32_e32 v1, 0x7f, v0
	v_xor_b32_e32 v2, 0x7e, v0
	v_or_b32_e32 v3, 1, v0
	v_and_b32_e32 v5, 0xfc, v5
	v_cmp_eq_u32_e32 vcc, 0, v11
	v_and_b32_e32 v6, 0xfc, v6
	v_cmp_gt_u32_e64 s[6:7], 2, v11
	v_and_b32_e32 v7, 0xfc, v7
	v_cmp_gt_u32_e64 s[8:9], 4, v11
	v_and_b32_e32 v8, 0xfc, v8
	v_cmp_gt_u32_e64 s[10:11], 8, v11
	v_and_b32_e32 v9, 0xfc, v9
	v_cmp_gt_u32_e64 s[12:13], 16, v11
	v_bitop3_b32 v10, v10, s1, v199 bitop3:0x6c
	v_cmp_gt_u32_e64 s[14:15], 32, v11
	v_readlane_b32 s5, v246, 59
	s_mov_b32 s21, 0xbfb8aa3b
	s_mov_b32 s30, 0x3f2aaaab
	s_mov_b32 s44, 0x3f317218
	s_mov_b32 s45, 0x7f800000
	s_mov_b32 s20, 0x33800000
	v_readlane_b32 s40, v243, 37
	v_readlane_b32 s41, v243, 38
	v_readlane_b32 s42, v243, 39
	v_readlane_b32 s43, v243, 40
	v_readlane_b32 s37, v243, 34
	v_readlane_b32 s38, v243, 35
	v_readlane_b32 s39, v243, 36
	s_and_b32 s98, s0, 0x7f
	s_and_b32 s32, s0, 0xffffff80
	s_cmp_lt_u32 s98, 64
	s_cselect_b64 s[100:101], -1, 0
	s_lshl_b32 s98, s98, 2
	v_cndmask_b32_e64 v33, v1, v0, s[100:101]
	v_cndmask_b32_e64 v34, v2, v3, s[100:101]
	v_or_b32_e32 v33, s32, v33
	v_or_b32_e32 v34, s32, v34
	v_lshl_add_u32 v33, v33, 9, s98
	v_lshl_add_u32 v34, v34, 9, s98
	v_mov_b32_e32 v35, s98
	global_load_dword v11, v35, s[42:43]
	global_load_dword v16, v35, s[40:41]
	global_load_dword v14, v33, s[4:5]
	global_load_dword v28, v34, s[4:5]
	s_waitcnt vmcnt(0)
.LBB0_327:
	s_and_b32 s2, s0, 0x7f
	s_and_b32 s1, s0, 0xffffff80
	s_cmp_lt_u32 s2, 64
	s_cselect_b64 s[16:17], -1, 0
	v_cndmask_b32_e64 v13, v1, v0, s[16:17]
	v_cndmask_b32_e64 v12, v2, v3, s[16:17]
	s_add_i32 s32, s0, s31
	s_cmpk_lt_i32 s32, 0x4000
	s_cselect_b32 s32, s32, s0
	s_and_b32 s98, s32, 0x7f
	s_and_b32 s32, s32, 0xffffff80
	s_cmp_lt_u32 s98, 64
	s_cselect_b64 s[100:101], -1, 0
	s_lshl_b32 s98, s98, 2
	v_cndmask_b32_e64 v33, v1, v0, s[100:101]
	v_cndmask_b32_e64 v34, v2, v3, s[100:101]
	v_or_b32_e32 v33, s32, v33
	v_or_b32_e32 v34, s32, v34
	v_lshl_add_u32 v33, v33, 9, s98
	v_lshl_add_u32 v34, v34, 9, s98
	v_mov_b32_e32 v35, s98
	global_load_dword v29, v35, s[42:43]
	global_load_dword v30, v35, s[40:41]
	global_load_dword v31, v33, s[4:5]
	global_load_dword v32, v34, s[4:5]
	s_lshl_b32 s2, s2, 14
	s_ashr_i32 s3, s1, 31
	v_mul_f32_e32 v11, 0x3fb8aa3b, v11
	v_exp_f32_e32 v11, v11
	v_add_f32_e32 v17, v16, v14
	v_max_f32_e32 v18, 0, v17
	s_add_u32 s1, s2, s1
	s_addc_u32 s2, 0, s3
	s_add_i32 s0, s0, s31
	s_cmpk_lt_i32 s0, 0x4000
	v_add_f32_e32 v16, v16, v28
	v_mul_f32_e64 v14, |v17|, s21
	v_exp_f32_e32 v17, v14
	s_nop 0
	v_add_f32_e32 v19, 1.0, v17
	v_add_f32_e32 v14, -1.0, v19
	v_sub_f32_e32 v15, v14, v19
	v_add_f32_e32 v15, 1.0, v15
	v_sub_f32_e32 v14, v17, v14
	v_add_f32_e32 v20, v14, v15
	v_frexp_mant_f32_e32 v14, v19
	v_cmp_gt_f32_e64 s[16:17], s30, v14
	v_cvt_f64_f32_e32 v[14:15], v19
	v_frexp_exp_i32_f64_e32 v14, v[14:15]
	v_subbrev_co_u32_e64 v14, s[16:17], 0, v14, s[16:17]
	v_sub_u32_e32 v15, 0, v14
	v_ldexp_f32 v19, v19, v15
	v_ldexp_f32 v15, v20, v15
	v_add_f32_e32 v20, -1.0, v19
	v_add_f32_e32 v21, 1.0, v20
	v_sub_f32_e32 v21, v19, v21
	v_add_f32_e32 v21, v15, v21
	v_add_f32_e32 v22, v20, v21
	v_sub_f32_e32 v20, v22, v20
	v_sub_f32_e32 v20, v21, v20
	v_add_f32_e32 v21, 1.0, v19
	v_add_f32_e32 v23, -1.0, v21
	v_sub_f32_e32 v19, v19, v23
	v_add_f32_e32 v15, v15, v19
	v_add_f32_e32 v19, v21, v15
	v_sub_f32_e32 v21, v19, v21
	v_sub_f32_e32 v15, v15, v21
	v_rcp_f32_e32 v21, v19
	v_cvt_f32_i32_e32 v14, v14
	v_cmp_neq_f32_e64 s[16:17], s45, v17
	v_mul_f32_e32 v23, v22, v21
	v_mul_f32_e32 v24, v19, v23
	v_fma_f32 v25, v23, v19, -v24
	v_fmac_f32_e32 v25, v23, v15
	v_add_f32_e32 v26, v24, v25
	v_sub_f32_e32 v27, v22, v26
	v_sub_f32_e32 v22, v22, v27
	v_sub_f32_e32 v24, v26, v24
	v_sub_f32_e32 v22, v22, v26
	v_add_f32_e32 v20, v20, v22
	v_sub_f32_e32 v22, v24, v25
	v_add_f32_e32 v20, v22, v20
	v_add_f32_e32 v22, v27, v20
	v_mul_f32_e32 v24, v21, v22
	v_mul_f32_e32 v25, v19, v24
	v_fma_f32 v19, v24, v19, -v25
	v_fmac_f32_e32 v19, v24, v15
	v_sub_f32_e32 v15, v27, v22
	v_add_f32_e32 v15, v20, v15
	v_add_f32_e32 v20, v25, v19
	v_sub_f32_e32 v26, v22, v20
	v_sub_f32_e32 v22, v22, v26
	v_sub_f32_e32 v25, v20, v25
	v_sub_f32_e32 v20, v22, v20
	v_add_f32_e32 v15, v15, v20
	v_sub_f32_e32 v19, v25, v19
	v_add_f32_e32 v15, v19, v15
	v_add_f32_e32 v19, v23, v24
	v_add_f32_e32 v15, v26, v15
	v_sub_f32_e32 v20, v19, v23
	v_mul_f32_e32 v15, v21, v15
	v_sub_f32_e32 v20, v24, v20
	v_add_f32_e32 v15, v20, v15
	v_mul_f32_e32 v23, 0x3f317218, v14
	v_add_f32_e32 v20, v19, v15
	v_fma_f32 v24, v14, s44, -v23
	v_mul_f32_e32 v21, v20, v20
	v_fmac_f32_e32 v24, 0xb102e308, v14
	v_sub_f32_e32 v14, v20, v19
	v_fmamk_f32 v22, v21, 0x3e9b6dac, v198
	v_sub_f32_e32 v14, v15, v14
	v_add_f32_e32 v15, v23, v24
	v_fmaak_f32 v22, v21, v22, 0x3f2aaada
	v_sub_f32_e32 v19, v15, v23
; __device__ __forceinline__ void conv_phase(const Params& P, const int pass, const int wvi) {
;     ...
;     float x0 = dtr[(size_t)(tb + e0) * 128 + dh] + db, x1 = dtr[(size_t)(tb + e1) * 128 + dh] + db;
;     float d0 = fmaxf(x0, 0.f) + log1pf(__expf(-fabsf(x0))), d1 = fmaxf(x1, 0.f) + log1pf(__expf(-fabsf(x1)));
;     float a0 = d0 * Ac, a1 = d1 * Ac;
;     float s = a0 + a1;
; #pragma unroll
;     for (int o = 1; o < 64; o <<= 1) { float v = shfl_src(s, (lane - o) & 63); if (lane >= o) s += v; }
;     dtt[(size_t)dh * PT + tb + e0] = d0; dtt[(size_t)dh * PT + tb + e1] = d1;
;     cum[(size_t)dh * PT + tb + e0] = s - a1; cum[(size_t)dh * PT + tb + e1] = s;
;     const float tot = shfl_src(s, 63), rs = shfl_src(s, (lane >> 4) * 16 + 15);
	v_ldexp_f32 v23, v20, 1
	v_mul_f32_e32 v20, v20, v21
	v_mul_f32_e32 v20, v20, v22
	v_add_f32_e32 v21, v23, v20
	v_sub_f32_e32 v22, v21, v23
	v_ldexp_f32 v14, v14, 1
	v_sub_f32_e32 v20, v20, v22
	v_add_f32_e32 v14, v14, v20
	v_add_f32_e32 v20, v21, v14
	v_sub_f32_e32 v21, v20, v21
	v_sub_f32_e32 v14, v14, v21
	v_add_f32_e32 v21, v15, v20
	v_sub_f32_e32 v22, v21, v15
	v_sub_f32_e32 v23, v21, v22
	v_sub_f32_e32 v19, v24, v19
	v_sub_f32_e32 v15, v15, v23
	v_sub_f32_e32 v20, v20, v22
	v_add_f32_e32 v15, v20, v15
	v_add_f32_e32 v20, v19, v14
	v_sub_f32_e32 v22, v20, v19
	v_sub_f32_e32 v23, v20, v22
	v_sub_f32_e32 v19, v19, v23
	v_sub_f32_e32 v14, v14, v22
	v_add_f32_e32 v15, v20, v15
	v_add_f32_e32 v14, v14, v19
	v_add_f32_e32 v19, v21, v15
	v_sub_f32_e32 v20, v19, v21
	v_sub_f32_e32 v15, v15, v20
	v_add_f32_e32 v14, v14, v15
	v_add_f32_e32 v14, v19, v14
	v_cndmask_b32_e64 v14, v200, v14, s[16:17]
	v_cmp_ngt_f32_e64 s[16:17], -1.0, v17
	v_max_f32_e32 v15, 0, v16
	v_mul_f32_e64 v16, |v16|, s21
	v_cndmask_b32_e64 v14, v201, v14, s[16:17]
	v_cmp_neq_f32_e64 s[16:17], -1.0, v17
	s_nop 1
	v_cndmask_b32_e64 v14, v202, v14, s[16:17]
	v_cmp_lt_f32_e64 s[16:17], |v17|, s20
	s_nop 1
	v_cndmask_b32_e64 v14, v14, v17, s[16:17]
	v_add_f32_e32 v14, v18, v14
	v_exp_f32_e32 v18, v16
	s_nop 0
	v_add_f32_e32 v19, 1.0, v18
	v_add_f32_e32 v16, -1.0, v19
	v_sub_f32_e32 v17, v16, v19
	v_add_f32_e32 v17, 1.0, v17
	v_sub_f32_e32 v16, v18, v16
	v_add_f32_e32 v20, v16, v17
	v_frexp_mant_f32_e32 v16, v19
	v_cmp_gt_f32_e64 s[16:17], s30, v16
	v_cvt_f64_f32_e32 v[16:17], v19
	v_frexp_exp_i32_f64_e32 v16, v[16:17]
	v_subbrev_co_u32_e64 v16, s[16:17], 0, v16, s[16:17]
	v_sub_u32_e32 v17, 0, v16
	v_ldexp_f32 v19, v19, v17
	v_ldexp_f32 v17, v20, v17
	v_add_f32_e32 v20, -1.0, v19
	v_add_f32_e32 v21, 1.0, v20
	v_sub_f32_e32 v21, v19, v21
	v_add_f32_e32 v21, v17, v21
	v_add_f32_e32 v22, v20, v21
	v_sub_f32_e32 v20, v22, v20
	v_sub_f32_e32 v20, v21, v20
	v_add_f32_e32 v21, 1.0, v19
	v_add_f32_e32 v23, -1.0, v21
	v_sub_f32_e32 v19, v19, v23
	v_add_f32_e32 v17, v17, v19
	v_add_f32_e32 v19, v21, v17
	v_sub_f32_e32 v21, v19, v21
	v_sub_f32_e32 v17, v17, v21
	v_rcp_f32_e32 v21, v19
	v_cvt_f32_i32_e32 v16, v16
	v_cmp_neq_f32_e64 s[16:17], s45, v18
	v_mul_f32_e32 v23, v22, v21
	v_mul_f32_e32 v24, v19, v23
	v_fma_f32 v25, v23, v19, -v24
	v_fmac_f32_e32 v25, v23, v17
	v_add_f32_e32 v26, v24, v25
	v_sub_f32_e32 v27, v22, v26
	v_sub_f32_e32 v22, v22, v27
	v_sub_f32_e32 v24, v26, v24
	v_sub_f32_e32 v22, v22, v26
	v_add_f32_e32 v20, v20, v22
	v_sub_f32_e32 v22, v24, v25
	v_add_f32_e32 v20, v22, v20
	v_add_f32_e32 v22, v27, v20
	v_mul_f32_e32 v24, v21, v22
	v_mul_f32_e32 v25, v19, v24
	v_fma_f32 v19, v24, v19, -v25
	v_fmac_f32_e32 v19, v24, v17
	v_sub_f32_e32 v17, v27, v22
	v_add_f32_e32 v17, v20, v17
	v_add_f32_e32 v20, v25, v19
	v_sub_f32_e32 v26, v22, v20
	v_sub_f32_e32 v22, v22, v26
	v_sub_f32_e32 v25, v20, v25
	v_sub_f32_e32 v20, v22, v20
	v_add_f32_e32 v17, v17, v20
	v_sub_f32_e32 v19, v25, v19
	v_add_f32_e32 v17, v19, v17
	v_add_f32_e32 v19, v23, v24
	v_add_f32_e32 v17, v26, v17
	v_sub_f32_e32 v20, v19, v23
	v_mul_f32_e32 v17, v21, v17
	v_sub_f32_e32 v20, v24, v20
	v_add_f32_e32 v17, v20, v17
	v_mul_f32_e32 v23, 0x3f317218, v16
	v_add_f32_e32 v20, v19, v17
	v_fma_f32 v24, v16, s44, -v23
	v_mul_f32_e32 v21, v20, v20
	v_fmac_f32_e32 v24, 0xb102e308, v16
	v_sub_f32_e32 v16, v20, v19
	v_fmamk_f32 v22, v21, 0x3e9b6dac, v198
	v_sub_f32_e32 v16, v17, v16
	v_add_f32_e32 v17, v23, v24
	v_fmaak_f32 v22, v21, v22, 0x3f2aaada
	v_sub_f32_e32 v19, v17, v23
	v_ldexp_f32 v23, v20, 1
	v_mul_f32_e32 v20, v20, v21
	v_mul_f32_e32 v20, v20, v22
	v_add_f32_e32 v21, v23, v20
	v_sub_f32_e32 v22, v21, v23
	v_ldexp_f32 v16, v16, 1
	v_sub_f32_e32 v20, v20, v22
	v_add_f32_e32 v16, v16, v20
	v_add_f32_e32 v20, v21, v16
	v_sub_f32_e32 v21, v20, v21
	v_sub_f32_e32 v16, v16, v21
	v_add_f32_e32 v21, v17, v20
	v_sub_f32_e32 v22, v21, v17
	v_sub_f32_e32 v23, v21, v22
	v_sub_f32_e32 v19, v24, v19
	v_sub_f32_e32 v17, v17, v23
	v_sub_f32_e32 v20, v20, v22
	v_add_f32_e32 v17, v20, v17
	v_add_f32_e32 v20, v19, v16
	v_sub_f32_e32 v22, v20, v19
	v_sub_f32_e32 v23, v20, v22
	v_sub_f32_e32 v19, v19, v23
	v_sub_f32_e32 v16, v16, v22
	v_add_f32_e32 v17, v20, v17
	v_add_f32_e32 v16, v16, v19
	v_add_f32_e32 v19, v21, v17
	v_sub_f32_e32 v20, v19, v21
	v_sub_f32_e32 v17, v17, v20
	v_add_f32_e32 v16, v16, v17
	v_add_f32_e32 v16, v19, v16
	v_cndmask_b32_e64 v16, v200, v16, s[16:17]
	v_cmp_ngt_f32_e64 s[16:17], -1.0, v18
	v_mov_b32_e32 v19, s2
	s_nop 0
	v_cndmask_b32_e64 v16, v201, v16, s[16:17]
	v_cmp_neq_f32_e64 s[16:17], -1.0, v18
	s_nop 1
	v_cndmask_b32_e64 v16, v202, v16, s[16:17]
	v_cmp_lt_f32_e64 s[16:17], |v18|, s20
	s_nop 1
	v_cndmask_b32_e64 v16, v16, v18, s[16:17]
	v_add_f32_e32 v15, v15, v16
	v_mul_f32_e32 v16, v11, v14
	v_fma_f32 v16, v15, -v11, -v16
	ds_bpermute_b32 v17, v5, v16
	v_or_b32_e32 v18, s1, v13
	v_lshlrev_b64 v[20:21], 2, v[18:19]
	v_or_b32_e32 v18, s1, v12
	v_lshlrev_b64 v[12:13], 2, v[18:19]
	s_waitcnt lgkmcnt(0)
; __device__ __forceinline__ void conv_phase(const Params& P, const int pass, const int wvi) {
;     ...
;     for (int o = 1; o < 64; o <<= 1) { float v = shfl_src(s, (lane - o) & 63); if (lane >= o) s += v; }
;     dtt[(size_t)dh * PT + tb + e0] = d0; dtt[(size_t)dh * PT + tb + e1] = d1;
;     cum[(size_t)dh * PT + tb + e0] = s - a1; cum[(size_t)dh * PT + tb + e1] = s;
;     const float tot = shfl_src(s, 63), rs = shfl_src(s, (lane >> 4) * 16 + 15);
;     float* wwp = (float*)(ws + OFF_WW);
;     float* eep = (float*)(ws + OFF_EE);
;     wwp[(size_t)dh * PT + tb + e0] = __expf(tot - (s - a1)) * d0; wwp[(size_t)dh * PT + tb + e1] = __expf(tot - s) * d1;
;     eep[(size_t)dh * PT + tb + e0] = __expf(rs - (s - a1)) * d0; eep[(size_t)dh * PT + tb + e1] = __expf(rs - s) * d1;
;   }
	v_add_f32_e32 v17, v16, v17
	v_cndmask_b32_e32 v16, v17, v16, vcc
	ds_bpermute_b32 v17, v6, v16
	v_lshl_add_u64 v[18:19], s[22:23], 0, v[12:13]
	global_store_dword v[18:19], v15, off
	v_lshl_add_u64 v[18:19], s[26:27], 0, v[20:21]
	v_lshl_add_u64 v[22:23], s[22:23], 0, v[20:21]
	s_waitcnt lgkmcnt(0)
	v_add_f32_e32 v17, v16, v17
	v_cndmask_b32_e64 v16, v17, v16, s[6:7]
	ds_bpermute_b32 v17, v7, v16
	global_store_dword v[22:23], v14, off
	s_waitcnt lgkmcnt(0)
	v_add_f32_e32 v17, v16, v17
	v_cndmask_b32_e64 v16, v17, v16, s[8:9]
	ds_bpermute_b32 v17, v8, v16
	s_waitcnt lgkmcnt(0)
	v_add_f32_e32 v17, v16, v17
	v_cndmask_b32_e64 v16, v17, v16, s[10:11]
	ds_bpermute_b32 v17, v9, v16
	s_waitcnt lgkmcnt(0)
	v_add_f32_e32 v17, v16, v17
	v_cndmask_b32_e64 v16, v17, v16, s[12:13]
	ds_bpermute_b32 v17, v10, v16
	s_waitcnt lgkmcnt(0)
	v_add_f32_e32 v17, v16, v17
	v_cndmask_b32_e64 v16, v17, v16, s[14:15]
	v_fma_f32 v11, v15, v11, v16
	global_store_dword v[18:19], v11, off
	v_lshl_add_u64 v[18:19], s[26:27], 0, v[12:13]
	v_readlane_b32 s1, v16, 63
	global_store_dword v[18:19], v16, off
	ds_bpermute_b32 v17, v4, v16
	v_sub_f32_e32 v18, s1, v11
	v_mul_f32_e32 v18, 0x3fb8aa3b, v18
	v_exp_f32_e32 v18, v18
	s_waitcnt lgkmcnt(0)
	v_sub_f32_e32 v11, v17, v11
	v_mul_f32_e32 v11, 0x3fb8aa3b, v11
	v_mul_f32_e32 v22, v14, v18
	v_lshl_add_u64 v[18:19], s[28:29], 0, v[20:21]
	global_store_dword v[18:19], v22, off
	v_sub_f32_e32 v18, s1, v16
	v_mul_f32_e32 v18, 0x3fb8aa3b, v18
	v_exp_f32_e32 v18, v18
	v_exp_f32_e32 v11, v11
	v_mul_f32_e32 v22, v15, v18
	v_lshl_add_u64 v[18:19], s[28:29], 0, v[12:13]
	global_store_dword v[18:19], v22, off
	v_mul_f32_e32 v11, v14, v11
	v_lshl_add_u64 v[18:19], s[34:35], 0, v[20:21]
	global_store_dword v[18:19], v11, off
	v_sub_f32_e32 v11, v17, v16
	v_mul_f32_e32 v11, 0x3fb8aa3b, v11
	v_exp_f32_e32 v11, v11
	v_lshl_add_u64 v[12:13], s[34:35], 0, v[12:13]
	v_mul_f32_e32 v11, v15, v11
	global_store_dword v[12:13], v11, off
	s_waitcnt vmcnt(8)
	v_mov_b32_e32 v11, v29
	v_mov_b32_e32 v16, v30
	v_mov_b32_e32 v14, v31
	v_mov_b32_e32 v28, v32
	s_cbranch_scc1 .LBB0_327
